# conv d-loop tails: barrier decision via two SCC branches instead of a materialised lane mask (wave-uniform branch test trimmed)
# baseline (speedup 1.0000x reference)
; #define LAS __attribute__((address_space(3)))
; #define LAUNDER_S(x) asm volatile("" : "+s"(x))
; #define CONV_DS(x) ({ int t_ = (x); LAUNDER_S(t_); t_; })
; __device__ __forceinline__ void conv_item(const Params& P, int slice, int item, LAS unsigned char* lds) {
;     ...
;     for (int d = dmin; d < lo0; ++d) { CONV_HEAD(); CONV_TAIL(); }
;     {
;       const LAS unsigned char* wb = CONV_WB(lo0 - dmin); const LAS unsigned char* bp0 = CONV_BPH(0, 0, lo0); const LAS unsigned char* bp1 = CONV_BPH(0, 1, lo0);
; #pragma unroll
;       for (int k = 0; k < 10; ++k) fa[k] = *(const LAS bf16x8*)(wb + 32 * (k - 3));
; #pragma unroll
;       for (int ks = 0; ks < 4; ++ks) { fb[ks] = *(const LAS bf16x8*)(bp0 + 64 * ks); fb[4 + ks] = *(const LAS bf16x8*)(bp1 + 64 * ks); }
;     }
;     const int hw = 16 >> nbsh;
;     ...
;     for (int d = CONV_DS(lo0); d < lo0 + hw; ++d) { CONV_HEADT(); CONV_TILESTEP(0, CONV_BPH(0, 0, d + 1), CONV_BPH(0, 1, d + 1), 1, CONV_WB(step + 1), 1, 1); CONV_TAIL(); }
;     for (int d = CONV_DS(lo0 + hw); d < lo1; ++d) { CONV_HEADT(); CONV_TILESTEP(0, CONV_BPH(0, 0, d + 1), CONV_BPH(0, 1, d + 1), 1, CONV_WB(step + 1), 3, 1); CONV_TAIL(); }
;     for (int d = CONV_DS(lo1); d < lo1 + hw; ++d) { CONV_HEADT(); CONV_TILESTEP(0, CONV_BPH(1, 0, d), CONV_BPH(1, 1, d), 0, Wn, 3, 1);
;       CONV_TILESTEP(1, CONV_NB1(0), CONV_NB1(1), 1, CONV_WB(step + 1), 1, 0); CONV_TAIL(); }
;     for (int d = CONV_DS(lo1 + hw); d <= hi0 - hw; ++d) { CONV_HEADT(); CONV_TILESTEP(0, CONV_BPH(1, 0, d), CONV_BPH(1, 1, d), 0, Wn, 3, 1);
;       CONV_TILESTEP(1, CONV_NB1(0), CONV_NB1(1), 1, CONV_WB(step + 1), 3, 0); CONV_TAIL(); }
;     for (int d = CONV_DS(hi0 - hw + 1); d <= hi0; ++d) { CONV_HEADT(); CONV_TILESTEP(0, CONV_BPH(1, 0, d), CONV_BPH(1, 1, d), 0, Wn, 2, 1);
;       CONV_TILESTEP(1, CONV_NB1(0), CONV_NB1(1), 1, CONV_WB(step + 1), 3, 0); CONV_TAIL(); }
;     for (int d = CONV_DS(hi0 + 1); d <= hi1 - hw; ++d) { CONV_HEADT(); CONV_TILESTEP(1, CONV_BPH(1, 0, d + 1), CONV_BPH(1, 1, d + 1), 1, CONV_WB(step + 1), 3, 1); CONV_TAIL(); }
;     for (int d = CONV_DS(hi1 - hw + 1); d <= hi1; ++d) { CONV_HEADT(); CONV_TILESTEP(1, CONV_BPH(1, 0, d + 1), CONV_BPH(1, 1, d + 1), 1, CONV_WB(step + 1), 2, 1); CONV_TAIL(); }
;     ...
;     { int dl_ = hi1 + 1; LAUNDER_S(dl_); for (int d = dl_; d < nblk; ++d) { CONV_HEAD(); CONV_TAIL(); } }
.LBB0_394:
	s_bitcmp1_b32 s16, 0
	s_cbranch_scc1 .Lcvb_1
	s_cmp_eq_u32 s57, s16
	s_cbranch_scc0 .LBB0_389
.Lcvb_1:
	s_waitcnt lgkmcnt(0)
	s_barrier
	s_branch .LBB0_389

; #define LAS __attribute__((address_space(3)))
; #define LAUNDER_S(x) asm volatile("" : "+s"(x))
; #define CONV_DS(x) ({ int t_ = (x); LAUNDER_S(t_); t_; })
; __device__ __forceinline__ void conv_item(const Params& P, int slice, int item, LAS unsigned char* lds) {
;     ...
;     for (int d = dmin; d < lo0; ++d) { CONV_HEAD(); CONV_TAIL(); }
;     {
;       const LAS unsigned char* wb = CONV_WB(lo0 - dmin); const LAS unsigned char* bp0 = CONV_BPH(0, 0, lo0); const LAS unsigned char* bp1 = CONV_BPH(0, 1, lo0);
; #pragma unroll
;       for (int k = 0; k < 10; ++k) fa[k] = *(const LAS bf16x8*)(wb + 32 * (k - 3));
; #pragma unroll
;       for (int ks = 0; ks < 4; ++ks) { fb[ks] = *(const LAS bf16x8*)(bp0 + 64 * ks); fb[4 + ks] = *(const LAS bf16x8*)(bp1 + 64 * ks); }
;     }
;     const int hw = 16 >> nbsh;
;     ...
;     for (int d = CONV_DS(lo0); d < lo0 + hw; ++d) { CONV_HEADT(); CONV_TILESTEP(0, CONV_BPH(0, 0, d + 1), CONV_BPH(0, 1, d + 1), 1, CONV_WB(step + 1), 1, 1); CONV_TAIL(); }
;     for (int d = CONV_DS(lo0 + hw); d < lo1; ++d) { CONV_HEADT(); CONV_TILESTEP(0, CONV_BPH(0, 0, d + 1), CONV_BPH(0, 1, d + 1), 1, CONV_WB(step + 1), 3, 1); CONV_TAIL(); }
;     for (int d = CONV_DS(lo1); d < lo1 + hw; ++d) { CONV_HEADT(); CONV_TILESTEP(0, CONV_BPH(1, 0, d), CONV_BPH(1, 1, d), 0, Wn, 3, 1);
;       CONV_TILESTEP(1, CONV_NB1(0), CONV_NB1(1), 1, CONV_WB(step + 1), 1, 0); CONV_TAIL(); }
;     for (int d = CONV_DS(lo1 + hw); d <= hi0 - hw; ++d) { CONV_HEADT(); CONV_TILESTEP(0, CONV_BPH(1, 0, d), CONV_BPH(1, 1, d), 0, Wn, 3, 1);
;       CONV_TILESTEP(1, CONV_NB1(0), CONV_NB1(1), 1, CONV_WB(step + 1), 3, 0); CONV_TAIL(); }
;     for (int d = CONV_DS(hi0 - hw + 1); d <= hi0; ++d) { CONV_HEADT(); CONV_TILESTEP(0, CONV_BPH(1, 0, d), CONV_BPH(1, 1, d), 0, Wn, 2, 1);
;       CONV_TILESTEP(1, CONV_NB1(0), CONV_NB1(1), 1, CONV_WB(step + 1), 3, 0); CONV_TAIL(); }
;     for (int d = CONV_DS(hi0 + 1); d <= hi1 - hw; ++d) { CONV_HEADT(); CONV_TILESTEP(1, CONV_BPH(1, 0, d + 1), CONV_BPH(1, 1, d + 1), 1, CONV_WB(step + 1), 3, 1); CONV_TAIL(); }
;     for (int d = CONV_DS(hi1 - hw + 1); d <= hi1; ++d) { CONV_HEADT(); CONV_TILESTEP(1, CONV_BPH(1, 0, d + 1), CONV_BPH(1, 1, d + 1), 1, CONV_WB(step + 1), 2, 1); CONV_TAIL(); }
;     ...
;     { int dl_ = hi1 + 1; LAUNDER_S(dl_); for (int d = dl_; d < nblk; ++d) { CONV_HEAD(); CONV_TAIL(); } }
.LBB0_401:
	s_bitcmp1_b32 s17, 0
	s_cbranch_scc1 .Lcvb_2
	s_cmp_eq_u32 s88, s16
	s_cbranch_scc0 .LBB0_398

; #define LAS __attribute__((address_space(3)))
; #define LAUNDER_S(x) asm volatile("" : "+s"(x))
; #define CONV_DS(x) ({ int t_ = (x); LAUNDER_S(t_); t_; })
; __device__ __forceinline__ void conv_item(const Params& P, int slice, int item, LAS unsigned char* lds) {
;     ...
;     for (int d = dmin; d < lo0; ++d) { CONV_HEAD(); CONV_TAIL(); }
;     {
;       const LAS unsigned char* wb = CONV_WB(lo0 - dmin); const LAS unsigned char* bp0 = CONV_BPH(0, 0, lo0); const LAS unsigned char* bp1 = CONV_BPH(0, 1, lo0);
; #pragma unroll
;       for (int k = 0; k < 10; ++k) fa[k] = *(const LAS bf16x8*)(wb + 32 * (k - 3));
; #pragma unroll
;       for (int ks = 0; ks < 4; ++ks) { fb[ks] = *(const LAS bf16x8*)(bp0 + 64 * ks); fb[4 + ks] = *(const LAS bf16x8*)(bp1 + 64 * ks); }
;     }
;     const int hw = 16 >> nbsh;
;     ...
;     for (int d = CONV_DS(lo0); d < lo0 + hw; ++d) { CONV_HEADT(); CONV_TILESTEP(0, CONV_BPH(0, 0, d + 1), CONV_BPH(0, 1, d + 1), 1, CONV_WB(step + 1), 1, 1); CONV_TAIL(); }
;     for (int d = CONV_DS(lo0 + hw); d < lo1; ++d) { CONV_HEADT(); CONV_TILESTEP(0, CONV_BPH(0, 0, d + 1), CONV_BPH(0, 1, d + 1), 1, CONV_WB(step + 1), 3, 1); CONV_TAIL(); }
;     for (int d = CONV_DS(lo1); d < lo1 + hw; ++d) { CONV_HEADT(); CONV_TILESTEP(0, CONV_BPH(1, 0, d), CONV_BPH(1, 1, d), 0, Wn, 3, 1);
;       CONV_TILESTEP(1, CONV_NB1(0), CONV_NB1(1), 1, CONV_WB(step + 1), 1, 0); CONV_TAIL(); }
;     for (int d = CONV_DS(lo1 + hw); d <= hi0 - hw; ++d) { CONV_HEADT(); CONV_TILESTEP(0, CONV_BPH(1, 0, d), CONV_BPH(1, 1, d), 0, Wn, 3, 1);
;       CONV_TILESTEP(1, CONV_NB1(0), CONV_NB1(1), 1, CONV_WB(step + 1), 3, 0); CONV_TAIL(); }
;     for (int d = CONV_DS(hi0 - hw + 1); d <= hi0; ++d) { CONV_HEADT(); CONV_TILESTEP(0, CONV_BPH(1, 0, d), CONV_BPH(1, 1, d), 0, Wn, 2, 1);
;       CONV_TILESTEP(1, CONV_NB1(0), CONV_NB1(1), 1, CONV_WB(step + 1), 3, 0); CONV_TAIL(); }
;     for (int d = CONV_DS(hi0 + 1); d <= hi1 - hw; ++d) { CONV_HEADT(); CONV_TILESTEP(1, CONV_BPH(1, 0, d + 1), CONV_BPH(1, 1, d + 1), 1, CONV_WB(step + 1), 3, 1); CONV_TAIL(); }
;     for (int d = CONV_DS(hi1 - hw + 1); d <= hi1; ++d) { CONV_HEADT(); CONV_TILESTEP(1, CONV_BPH(1, 0, d + 1), CONV_BPH(1, 1, d + 1), 1, CONV_WB(step + 1), 2, 1); CONV_TAIL(); }
;     ...
;     { int dl_ = hi1 + 1; LAUNDER_S(dl_); for (int d = dl_; d < nblk; ++d) { CONV_HEAD(); CONV_TAIL(); } }
.LBB0_417:
	s_bitcmp1_b32 s68, 0
	s_cbranch_scc1 .Lcvb_4
	s_cmp_eq_u32 s88, s16
	s_cbranch_scc0 .LBB0_414

; #define LAS __attribute__((address_space(3)))
; #define LAUNDER_S(x) asm volatile("" : "+s"(x))
; #define CONV_DS(x) ({ int t_ = (x); LAUNDER_S(t_); t_; })
; __device__ __forceinline__ void conv_item(const Params& P, int slice, int item, LAS unsigned char* lds) {
;     ...
;     for (int d = dmin; d < lo0; ++d) { CONV_HEAD(); CONV_TAIL(); }
;     {
;       const LAS unsigned char* wb = CONV_WB(lo0 - dmin); const LAS unsigned char* bp0 = CONV_BPH(0, 0, lo0); const LAS unsigned char* bp1 = CONV_BPH(0, 1, lo0);
; #pragma unroll
;       for (int k = 0; k < 10; ++k) fa[k] = *(const LAS bf16x8*)(wb + 32 * (k - 3));
; #pragma unroll
;       for (int ks = 0; ks < 4; ++ks) { fb[ks] = *(const LAS bf16x8*)(bp0 + 64 * ks); fb[4 + ks] = *(const LAS bf16x8*)(bp1 + 64 * ks); }
;     }
;     const int hw = 16 >> nbsh;
;     ...
;     for (int d = CONV_DS(lo0); d < lo0 + hw; ++d) { CONV_HEADT(); CONV_TILESTEP(0, CONV_BPH(0, 0, d + 1), CONV_BPH(0, 1, d + 1), 1, CONV_WB(step + 1), 1, 1); CONV_TAIL(); }
;     for (int d = CONV_DS(lo0 + hw); d < lo1; ++d) { CONV_HEADT(); CONV_TILESTEP(0, CONV_BPH(0, 0, d + 1), CONV_BPH(0, 1, d + 1), 1, CONV_WB(step + 1), 3, 1); CONV_TAIL(); }
;     for (int d = CONV_DS(lo1); d < lo1 + hw; ++d) { CONV_HEADT(); CONV_TILESTEP(0, CONV_BPH(1, 0, d), CONV_BPH(1, 1, d), 0, Wn, 3, 1);
;       CONV_TILESTEP(1, CONV_NB1(0), CONV_NB1(1), 1, CONV_WB(step + 1), 1, 0); CONV_TAIL(); }
;     for (int d = CONV_DS(lo1 + hw); d <= hi0 - hw; ++d) { CONV_HEADT(); CONV_TILESTEP(0, CONV_BPH(1, 0, d), CONV_BPH(1, 1, d), 0, Wn, 3, 1);
;       CONV_TILESTEP(1, CONV_NB1(0), CONV_NB1(1), 1, CONV_WB(step + 1), 3, 0); CONV_TAIL(); }
;     for (int d = CONV_DS(hi0 - hw + 1); d <= hi0; ++d) { CONV_HEADT(); CONV_TILESTEP(0, CONV_BPH(1, 0, d), CONV_BPH(1, 1, d), 0, Wn, 2, 1);
;       CONV_TILESTEP(1, CONV_NB1(0), CONV_NB1(1), 1, CONV_WB(step + 1), 3, 0); CONV_TAIL(); }
;     for (int d = CONV_DS(hi0 + 1); d <= hi1 - hw; ++d) { CONV_HEADT(); CONV_TILESTEP(1, CONV_BPH(1, 0, d + 1), CONV_BPH(1, 1, d + 1), 1, CONV_WB(step + 1), 3, 1); CONV_TAIL(); }
;     for (int d = CONV_DS(hi1 - hw + 1); d <= hi1; ++d) { CONV_HEADT(); CONV_TILESTEP(1, CONV_BPH(1, 0, d + 1), CONV_BPH(1, 1, d + 1), 1, CONV_WB(step + 1), 2, 1); CONV_TAIL(); }
;     ...
;     { int dl_ = hi1 + 1; LAUNDER_S(dl_); for (int d = dl_; d < nblk; ++d) { CONV_HEAD(); CONV_TAIL(); } }
.LBB0_424:
	s_add_i32 s17, s89, s17
	s_bitcmp1_b32 s69, 0
	s_cbranch_scc1 .Lcvb_5
	s_cmp_eq_u32 s17, -1
	s_cbranch_scc0 .LBB0_426
.Lcvb_5:
	s_waitcnt lgkmcnt(0)
	s_barrier

; #define LAS __attribute__((address_space(3)))
; #define LAUNDER_S(x) asm volatile("" : "+s"(x))
; #define CONV_DS(x) ({ int t_ = (x); LAUNDER_S(t_); t_; })
; __device__ __forceinline__ void conv_item(const Params& P, int slice, int item, LAS unsigned char* lds) {
;     ...
;     for (int d = dmin; d < lo0; ++d) { CONV_HEAD(); CONV_TAIL(); }
;     {
;       const LAS unsigned char* wb = CONV_WB(lo0 - dmin); const LAS unsigned char* bp0 = CONV_BPH(0, 0, lo0); const LAS unsigned char* bp1 = CONV_BPH(0, 1, lo0);
; #pragma unroll
;       for (int k = 0; k < 10; ++k) fa[k] = *(const LAS bf16x8*)(wb + 32 * (k - 3));
; #pragma unroll
;       for (int ks = 0; ks < 4; ++ks) { fb[ks] = *(const LAS bf16x8*)(bp0 + 64 * ks); fb[4 + ks] = *(const LAS bf16x8*)(bp1 + 64 * ks); }
;     }
;     const int hw = 16 >> nbsh;
;     ...
;     for (int d = CONV_DS(lo0); d < lo0 + hw; ++d) { CONV_HEADT(); CONV_TILESTEP(0, CONV_BPH(0, 0, d + 1), CONV_BPH(0, 1, d + 1), 1, CONV_WB(step + 1), 1, 1); CONV_TAIL(); }
;     for (int d = CONV_DS(lo0 + hw); d < lo1; ++d) { CONV_HEADT(); CONV_TILESTEP(0, CONV_BPH(0, 0, d + 1), CONV_BPH(0, 1, d + 1), 1, CONV_WB(step + 1), 3, 1); CONV_TAIL(); }
;     for (int d = CONV_DS(lo1); d < lo1 + hw; ++d) { CONV_HEADT(); CONV_TILESTEP(0, CONV_BPH(1, 0, d), CONV_BPH(1, 1, d), 0, Wn, 3, 1);
;       CONV_TILESTEP(1, CONV_NB1(0), CONV_NB1(1), 1, CONV_WB(step + 1), 1, 0); CONV_TAIL(); }
;     for (int d = CONV_DS(lo1 + hw); d <= hi0 - hw; ++d) { CONV_HEADT(); CONV_TILESTEP(0, CONV_BPH(1, 0, d), CONV_BPH(1, 1, d), 0, Wn, 3, 1);
;       CONV_TILESTEP(1, CONV_NB1(0), CONV_NB1(1), 1, CONV_WB(step + 1), 3, 0); CONV_TAIL(); }
;     for (int d = CONV_DS(hi0 - hw + 1); d <= hi0; ++d) { CONV_HEADT(); CONV_TILESTEP(0, CONV_BPH(1, 0, d), CONV_BPH(1, 1, d), 0, Wn, 2, 1);
;       CONV_TILESTEP(1, CONV_NB1(0), CONV_NB1(1), 1, CONV_WB(step + 1), 3, 0); CONV_TAIL(); }
;     for (int d = CONV_DS(hi0 + 1); d <= hi1 - hw; ++d) { CONV_HEADT(); CONV_TILESTEP(1, CONV_BPH(1, 0, d + 1), CONV_BPH(1, 1, d + 1), 1, CONV_WB(step + 1), 3, 1); CONV_TAIL(); }
;     for (int d = CONV_DS(hi1 - hw + 1); d <= hi1; ++d) { CONV_HEADT(); CONV_TILESTEP(1, CONV_BPH(1, 0, d + 1), CONV_BPH(1, 1, d + 1), 1, CONV_WB(step + 1), 2, 1); CONV_TAIL(); }
;     ...
;     { int dl_ = hi1 + 1; LAUNDER_S(dl_); for (int d = dl_; d < nblk; ++d) { CONV_HEAD(); CONV_TAIL(); } }
.LBB0_434:
	s_bitcmp1_b32 s70, 0
	s_cbranch_scc1 .Lcvb_6
	s_cmp_eq_u32 s88, s68
	s_cbranch_scc0 .LBB0_431

; #define LAS __attribute__((address_space(3)))
; #define LAUNDER_S(x) asm volatile("" : "+s"(x))
; #define CONV_DS(x) ({ int t_ = (x); LAUNDER_S(t_); t_; })
; __device__ __forceinline__ void conv_item(const Params& P, int slice, int item, LAS unsigned char* lds) {
;     ...
;     for (int d = dmin; d < lo0; ++d) { CONV_HEAD(); CONV_TAIL(); }
;     {
;       const LAS unsigned char* wb = CONV_WB(lo0 - dmin); const LAS unsigned char* bp0 = CONV_BPH(0, 0, lo0); const LAS unsigned char* bp1 = CONV_BPH(0, 1, lo0);
; #pragma unroll
;       for (int k = 0; k < 10; ++k) fa[k] = *(const LAS bf16x8*)(wb + 32 * (k - 3));
; #pragma unroll
;       for (int ks = 0; ks < 4; ++ks) { fb[ks] = *(const LAS bf16x8*)(bp0 + 64 * ks); fb[4 + ks] = *(const LAS bf16x8*)(bp1 + 64 * ks); }
;     }
;     const int hw = 16 >> nbsh;
;     ...
;     for (int d = CONV_DS(lo0); d < lo0 + hw; ++d) { CONV_HEADT(); CONV_TILESTEP(0, CONV_BPH(0, 0, d + 1), CONV_BPH(0, 1, d + 1), 1, CONV_WB(step + 1), 1, 1); CONV_TAIL(); }
;     for (int d = CONV_DS(lo0 + hw); d < lo1; ++d) { CONV_HEADT(); CONV_TILESTEP(0, CONV_BPH(0, 0, d + 1), CONV_BPH(0, 1, d + 1), 1, CONV_WB(step + 1), 3, 1); CONV_TAIL(); }
;     for (int d = CONV_DS(lo1); d < lo1 + hw; ++d) { CONV_HEADT(); CONV_TILESTEP(0, CONV_BPH(1, 0, d), CONV_BPH(1, 1, d), 0, Wn, 3, 1);
;       CONV_TILESTEP(1, CONV_NB1(0), CONV_NB1(1), 1, CONV_WB(step + 1), 1, 0); CONV_TAIL(); }
;     for (int d = CONV_DS(lo1 + hw); d <= hi0 - hw; ++d) { CONV_HEADT(); CONV_TILESTEP(0, CONV_BPH(1, 0, d), CONV_BPH(1, 1, d), 0, Wn, 3, 1);
;       CONV_TILESTEP(1, CONV_NB1(0), CONV_NB1(1), 1, CONV_WB(step + 1), 3, 0); CONV_TAIL(); }
;     for (int d = CONV_DS(hi0 - hw + 1); d <= hi0; ++d) { CONV_HEADT(); CONV_TILESTEP(0, CONV_BPH(1, 0, d), CONV_BPH(1, 1, d), 0, Wn, 2, 1);
;       CONV_TILESTEP(1, CONV_NB1(0), CONV_NB1(1), 1, CONV_WB(step + 1), 3, 0); CONV_TAIL(); }
;     for (int d = CONV_DS(hi0 + 1); d <= hi1 - hw; ++d) { CONV_HEADT(); CONV_TILESTEP(1, CONV_BPH(1, 0, d + 1), CONV_BPH(1, 1, d + 1), 1, CONV_WB(step + 1), 3, 1); CONV_TAIL(); }
;     for (int d = CONV_DS(hi1 - hw + 1); d <= hi1; ++d) { CONV_HEADT(); CONV_TILESTEP(1, CONV_BPH(1, 0, d + 1), CONV_BPH(1, 1, d + 1), 1, CONV_WB(step + 1), 2, 1); CONV_TAIL(); }
;     ...
;     { int dl_ = hi1 + 1; LAUNDER_S(dl_); for (int d = dl_; d < nblk; ++d) { CONV_HEAD(); CONV_TAIL(); } }
.LBB0_441:
	s_add_i32 s68, s89, s16
	s_bitcmp1_b32 s17, 0
	s_cbranch_scc1 .Lcvb_7
	s_cmp_eq_u32 s68, -1
	s_cbranch_scc0 .LBB0_438
